# MLA attention: K/V tiles double-buffered in LDS, one barrier per tile, compute lags the LDS write by one tile
# baseline (speedup 1.0000x reference)
.LBB0_1598:
	v_and_b32_e32 v226, 0xffff, v226
	v_and_b32_e32 v227, 0xffff, v227
	v_and_b32_e32 v229, 0xffff, v229
	v_and_b32_e32 v230, 0xffff, v230
	v_and_b32_e32 v231, 0xffff, v231
	v_and_b32_e32 v232, 0xffff, v232
	v_and_b32_e32 v233, 0xffff, v233
	s_ashr_i32 s29, s23, 31
	s_lshr_b32 s29, s29, 25
	s_add_i32 s29, s23, s29
	s_ashr_i32 s31, s29, 7
	s_and_b32 s29, s29, 0xff80
	s_sub_i32 s29, s23, s29
	s_bfe_i32 s54, s29, 0x80000
	s_bfe_u32 s54, s54, 0x3000c
	s_add_i32 s54, s29, s54
	s_bfe_i32 s55, s54, 0x80000
	s_and_b32 s54, s54, 0xf8
	s_sub_i32 s29, s29, s54
	s_sext_i32_i8 s56, s29
	s_lshl_b32 s29, s31, 2
	s_sext_i32_i16 s55, s55
	s_lshr_b32 s29, 0x10235467, s29
	s_and_b32 s31, s29, 7
	s_lshl_b32 s29, s55, 8
	s_and_b32 s29, s29, 0xfffff800
	s_lshl_b32 s54, s31, 8
	s_or_b32 s54, s29, s54
	v_add_u32_e32 v2, s54, v219
	v_ashrrev_i32_e32 v3, 31, v2
	v_lshlrev_b64 v[4:5], 10, v[2:3]
	s_lshl_b32 s54, s56, 6
	v_lshl_add_u64 v[4:5], s[26:27], 0, v[4:5]
	s_ashr_i32 s55, s54, 31
	v_lshl_add_u64 v[4:5], s[54:55], 1, v[4:5]
	v_lshlrev_b64 v[200:201], 11, v[2:3]
	s_lshl_b32 s54, s56, 7
	v_lshl_add_u64 v[2:3], s[24:25], 0, v[200:201]
	s_ashr_i32 s55, s54, 31
	v_lshl_add_u64 v[2:3], s[54:55], 1, v[2:3]
	v_lshl_add_u64 v[2:3], v[2:3], 0, v[166:167]
	global_load_dwordx4 v[142:145], v[2:3], off
	global_load_dwordx4 v[138:141], v[2:3], off offset:32
	global_load_dwordx4 v[134:137], v[2:3], off offset:64
	global_load_dwordx4 v[130:133], v[2:3], off offset:96
	global_load_dwordx4 v[126:129], v[2:3], off offset:128
	global_load_dwordx4 v[122:125], v[2:3], off offset:160
	global_load_dwordx4 v[118:121], v[2:3], off offset:192
	global_load_dwordx4 v[114:117], v[2:3], off offset:224
	v_lshl_add_u64 v[2:3], v[4:5], 0, v[166:167]
	global_load_dwordx4 v[110:113], v[2:3], off
	global_load_dwordx4 v[106:109], v[2:3], off offset:32
	global_load_dwordx4 v[102:105], v[2:3], off offset:64
	global_load_dwordx4 v[98:101], v[2:3], off offset:96
	v_add_u32_e32 v4, s29, v220
	v_ashrrev_i32_e32 v5, 31, v4
	v_lshlrev_b64 v[2:3], 7, v[4:5]
	s_and_saveexec_b64 s[56:57], s[6:7]
	s_xor_b64 s[56:57], exec, s[56:57]
	v_lshl_add_u64 v[6:7], v[168:169], 0, v[2:3]
	v_lshl_add_u64 v[6:7], v[6:7], 0, s[50:51]
	s_or_saveexec_b64 s[56:57], s[56:57]
	v_lshlrev_b64 v[4:5], 11, v[4:5]
	s_xor_b64 exec, exec, s[56:57]
	v_lshl_add_u64 v[6:7], s[42:43], 0, v[4:5]
	v_lshl_add_u64 v[6:7], s[54:55], 1, v[6:7]
	v_lshl_add_u64 v[6:7], v[170:171], 1, v[6:7]
	s_or_b64 exec, exec, s[56:57]
	global_load_dwordx4 v[146:149], v[6:7], off
	v_add_u32_e32 v8, s29, v221
	v_ashrrev_i32_e32 v9, 31, v8
	v_lshlrev_b64 v[6:7], 7, v[8:9]
	s_and_saveexec_b64 s[56:57], s[10:11]
	s_xor_b64 s[56:57], exec, s[56:57]
	v_lshl_add_u64 v[10:11], v[172:173], 0, v[6:7]
	v_lshl_add_u64 v[10:11], v[10:11], 0, s[50:51]
	s_or_saveexec_b64 s[56:57], s[56:57]
	v_lshlrev_b64 v[8:9], 11, v[8:9]
	s_xor_b64 exec, exec, s[56:57]
	v_lshl_add_u64 v[10:11], s[42:43], 0, v[8:9]
	v_lshl_add_u64 v[10:11], s[54:55], 1, v[10:11]
	v_lshl_add_u64 v[10:11], v[174:175], 1, v[10:11]
	s_or_b64 exec, exec, s[56:57]
	global_load_dwordx4 v[150:153], v[10:11], off
	v_add_u32_e32 v16, s29, v222
	v_ashrrev_i32_e32 v17, 31, v16
	v_lshlrev_b64 v[10:11], 7, v[16:17]
	v_lshlrev_b64 v[12:13], 11, v[16:17]
	s_and_saveexec_b64 s[56:57], s[14:15]
	s_xor_b64 s[56:57], exec, s[56:57]
	v_lshlrev_b64 v[10:11], 7, v[16:17]
	v_lshl_add_u64 v[12:13], v[176:177], 0, v[10:11]
	v_lshl_add_u64 v[14:15], v[12:13], 0, s[50:51]
	v_lshlrev_b64 v[12:13], 11, v[16:17]
	s_andn2_saveexec_b64 s[56:57], s[56:57]
	v_lshl_add_u64 v[14:15], s[42:43], 0, v[12:13]
	v_lshl_add_u64 v[14:15], s[54:55], 1, v[14:15]
	v_lshl_add_u64 v[14:15], v[178:179], 1, v[14:15]
	s_or_b64 exec, exec, s[56:57]
	global_load_dwordx4 v[154:157], v[14:15], off
	v_add_u32_e32 v14, s29, v223
	v_ashrrev_i32_e32 v15, 31, v14
	v_add_u32_e32 v18, s29, v224
	v_lshlrev_b64 v[14:15], 11, v[14:15]
	v_ashrrev_i32_e32 v19, 31, v18
	v_lshl_add_u64 v[16:17], s[44:45], 0, v[14:15]
	s_lshl_b64 s[56:57], s[54:55], 1
	v_lshlrev_b64 v[18:19], 11, v[18:19]
	v_lshl_add_u64 v[16:17], v[16:17], 0, s[56:57]
	v_lshl_add_u64 v[20:21], s[44:45], 0, v[18:19]
	v_lshl_add_u64 v[16:17], v[180:181], 1, v[16:17]
	v_lshl_add_u64 v[20:21], v[20:21], 0, s[56:57]
	v_lshl_add_u64 v[20:21], v[182:183], 1, v[20:21]
	global_load_dwordx4 v[162:165], v[16:17], off
	global_load_dwordx4 v[158:161], v[20:21], off
	v_lshl_add_u64 v[16:17], v[18:19], 0, s[56:57]
	v_lshl_add_u64 v[202:203], v[184:185], 0, v[16:17]
	v_lshl_add_u64 v[14:15], v[14:15], 0, s[56:57]
	v_lshl_add_u64 v[12:13], v[12:13], 0, s[56:57]
	v_lshl_add_u64 v[8:9], v[8:9], 0, s[56:57]
	v_lshl_add_u64 v[4:5], v[4:5], 0, s[56:57]
	v_mov_b32_e32 v16, v167
	v_mov_b32_e32 v17, v167
	s_lshl_b32 s29, s31, 2
	s_lshl_b32 s31, s31, 19
	v_lshl_add_u64 v[204:205], v[186:187], 0, v[14:15]
	v_lshl_add_u64 v[206:207], v[188:189], 0, v[12:13]
	v_lshl_add_u64 v[208:209], v[190:191], 0, v[10:11]
	v_lshl_add_u64 v[210:211], v[192:193], 0, v[8:9]
	v_lshl_add_u64 v[212:213], v[194:195], 0, v[6:7]
	v_lshl_add_u64 v[214:215], v[196:197], 0, v[4:5]
	v_lshl_add_u64 v[216:217], v[198:199], 0, v[2:3]
	v_mov_b32_e32 v2, v167
	v_mov_b32_e32 v3, v167
	v_mov_b32_e32 v4, v167
	v_mov_b32_e32 v5, v167
	v_mov_b32_e32 v6, v167
	v_mov_b32_e32 v7, v167
	v_mov_b32_e32 v8, v167
	v_mov_b32_e32 v9, v167
	v_mov_b32_e32 v10, v167
	v_mov_b32_e32 v11, v167
	v_mov_b32_e32 v12, v167
	v_mov_b32_e32 v13, v167
	v_mov_b32_e32 v14, v167
	v_mov_b32_e32 v15, v167
	v_mov_b64_e32 v[32:33], v[16:17]
	v_mov_b64_e32 v[48:49], v[16:17]
	v_mov_b64_e32 v[64:65], v[16:17]
	s_add_i32 s29, s29, s3
	s_or_b32 s31, s31, 0x60000
	s_mov_b32 s58, 0
	v_mov_b32_e32 v218, 0xf149f2ca
	v_mov_b32_e32 v234, 0
	s_mov_b64 s[56:57], 0
	v_mov_b64_e32 v[30:31], v[14:15]
	v_mov_b64_e32 v[28:29], v[12:13]
	v_mov_b64_e32 v[26:27], v[10:11]
	v_mov_b64_e32 v[24:25], v[8:9]
	v_mov_b64_e32 v[22:23], v[6:7]
	v_mov_b64_e32 v[20:21], v[4:5]
	v_mov_b64_e32 v[18:19], v[2:3]
	v_mov_b64_e32 v[46:47], v[14:15]
	v_mov_b64_e32 v[44:45], v[12:13]
	v_mov_b64_e32 v[42:43], v[10:11]
	v_mov_b64_e32 v[40:41], v[8:9]
	v_mov_b64_e32 v[38:39], v[6:7]
	v_mov_b64_e32 v[36:37], v[4:5]
	v_mov_b64_e32 v[34:35], v[2:3]
	v_mov_b64_e32 v[62:63], v[14:15]
	v_mov_b64_e32 v[60:61], v[12:13]
	v_mov_b64_e32 v[58:59], v[10:11]
	v_mov_b64_e32 v[56:57], v[8:9]
	v_mov_b64_e32 v[54:55], v[6:7]
	v_mov_b64_e32 v[52:53], v[4:5]
	v_mov_b64_e32 v[50:51], v[2:3]
.LBB0_1611:
	v_lshl_add_u64 v[66:67], v[214:215], 0, s[56:57]
	v_cndmask_b32_e64 v67, v217, v67, s[4:5]
	v_cndmask_b32_e64 v66, v216, v66, s[4:5]
	v_xor_b32_e32 v226, 0x10000, v226
	v_xor_b32_e32 v227, 0x10000, v227
	s_waitcnt lgkmcnt(0)
	s_barrier
	s_waitcnt vmcnt(4)
	ds_write_b128 v229, v[146:149]
	s_waitcnt vmcnt(3)
	ds_write_b128 v230, v[150:153]
	s_waitcnt vmcnt(2)
	ds_write_b128 v231, v[154:157]
	s_waitcnt vmcnt(1)
	ds_write_b128 v232, v[162:165] offset:25600
	s_waitcnt vmcnt(0)
	ds_write_b128 v233, v[158:161] offset:25600
	v_xor_b32_e32 v229, 0x10000, v229
	v_xor_b32_e32 v230, 0x10000, v230
	v_xor_b32_e32 v231, 0x10000, v231
	v_xor_b32_e32 v232, 0x10000, v232
	v_xor_b32_e32 v233, 0x10000, v233
	global_load_dwordx4 v[146:149], v[66:67], off
	v_lshl_add_u64 v[66:67], v[210:211], 0, s[56:57]
	v_cndmask_b32_e64 v67, v213, v67, s[8:9]
	v_cndmask_b32_e64 v66, v212, v66, s[8:9]
	global_load_dwordx4 v[150:153], v[66:67], off
	v_lshl_add_u64 v[66:67], v[206:207], 0, s[56:57]
	v_cndmask_b32_e64 v67, v209, v67, s[12:13]
	v_cndmask_b32_e64 v66, v208, v66, s[12:13]
	global_load_dwordx4 v[154:157], v[66:67], off
	v_lshl_add_u64 v[66:67], v[204:205], 0, s[56:57]
	v_lshl_add_u64 v[68:69], v[202:203], 0, s[56:57]
	global_load_dwordx4 v[162:165], v[66:67], off
	global_load_dwordx4 v[158:161], v[68:69], off
	s_add_i32 s99, s58, -1
	s_cmp_lt_i32 s99, 0
	s_cbranch_scc1 .LBB0_1615
	s_cmp_gt_i32 s99, s29
	s_cbranch_scc1 .LBB0_1615
	v_add_u32_e32 v235, v226, v225
	ds_read_b128 v[66:69], v235
	ds_read_b128 v[236:239], v235 offset:32
	ds_read_b128 v[70:73], v235 offset:12800
	ds_read_b128 v[244:247], v235 offset:12832
	s_waitcnt lgkmcnt(3)
	v_mfma_f32_32x32x16_bf16 v[82:97], v[66:69], v[142:145], 0
	ds_read_b128 v[248:251], v235 offset:64
	ds_read_b128 v[252:255], v235 offset:12864
	s_waitcnt lgkmcnt(3)
	v_mfma_f32_32x32x16_bf16 v[66:81], v[70:73], v[142:145], 0
	v_mfma_f32_32x32x16_bf16 v[82:97], v[236:239], v[138:141], v[82:97]
	s_waitcnt lgkmcnt(2)
	v_mfma_f32_32x32x16_bf16 v[66:81], v[244:247], v[138:141], v[66:81]
	ds_read_b128 v[236:239], v235 offset:96
	ds_read_b128 v[244:247], v235 offset:12896
	s_waitcnt lgkmcnt(3)
	v_mfma_f32_32x32x16_bf16 v[82:97], v[248:251], v[134:137], v[82:97]
	s_waitcnt lgkmcnt(2)
	v_mfma_f32_32x32x16_bf16 v[66:81], v[252:255], v[134:137], v[66:81]
	ds_read_b128 v[248:251], v235 offset:128
	ds_read_b128 v[252:255], v235 offset:12928
	s_waitcnt lgkmcnt(3)
	v_mfma_f32_32x32x16_bf16 v[82:97], v[236:239], v[130:133], v[82:97]
	s_waitcnt lgkmcnt(2)
	v_mfma_f32_32x32x16_bf16 v[66:81], v[244:247], v[130:133], v[66:81]
	ds_read_b128 v[236:239], v235 offset:160
	ds_read_b128 v[244:247], v235 offset:12960
	s_waitcnt lgkmcnt(3)
	v_mfma_f32_32x32x16_bf16 v[82:97], v[248:251], v[126:129], v[82:97]
	s_waitcnt lgkmcnt(2)
	v_mfma_f32_32x32x16_bf16 v[66:81], v[252:255], v[126:129], v[66:81]
	ds_read_b128 v[248:251], v235 offset:192
	ds_read_b128 v[252:255], v235 offset:12992
	s_waitcnt lgkmcnt(3)
	v_mfma_f32_32x32x16_bf16 v[82:97], v[236:239], v[122:125], v[82:97]
	s_waitcnt lgkmcnt(2)
	v_mfma_f32_32x32x16_bf16 v[66:81], v[244:247], v[122:125], v[66:81]
	ds_read_b128 v[236:239], v235 offset:224
	ds_read_b128 v[244:247], v235 offset:13024
	s_waitcnt lgkmcnt(3)
	v_mfma_f32_32x32x16_bf16 v[82:97], v[248:251], v[118:121], v[82:97]
	s_waitcnt lgkmcnt(2)
	v_mfma_f32_32x32x16_bf16 v[66:81], v[252:255], v[118:121], v[66:81]
	ds_read_b128 v[248:251], v235 offset:256
	ds_read_b128 v[252:255], v235 offset:13056
	s_waitcnt lgkmcnt(3)
	v_mfma_f32_32x32x16_bf16 v[82:97], v[236:239], v[114:117], v[82:97]
	s_waitcnt lgkmcnt(2)
	v_mfma_f32_32x32x16_bf16 v[66:81], v[244:247], v[114:117], v[66:81]
	ds_read_b128 v[236:239], v235 offset:288
	ds_read_b128 v[244:247], v235 offset:13088
	s_waitcnt lgkmcnt(3)
	v_mfma_f32_32x32x16_bf16 v[82:97], v[248:251], v[110:113], v[82:97]
	s_waitcnt lgkmcnt(2)
	v_mfma_f32_32x32x16_bf16 v[66:81], v[252:255], v[110:113], v[66:81]
	ds_read_b128 v[248:251], v235 offset:320
	ds_read_b128 v[252:255], v235 offset:13120
	s_waitcnt lgkmcnt(3)
	v_mfma_f32_32x32x16_bf16 v[82:97], v[236:239], v[106:109], v[82:97]
	s_waitcnt lgkmcnt(2)
	v_mfma_f32_32x32x16_bf16 v[66:81], v[244:247], v[106:109], v[66:81]
	ds_read_b128 v[236:239], v235 offset:352
	ds_read_b128 v[244:247], v235 offset:13152
	s_waitcnt lgkmcnt(3)
	v_mfma_f32_32x32x16_bf16 v[82:97], v[248:251], v[102:105], v[82:97]
	s_waitcnt lgkmcnt(2)
	v_mfma_f32_32x32x16_bf16 v[66:81], v[252:255], v[102:105], v[66:81]
	s_waitcnt lgkmcnt(1)
	v_mfma_f32_32x32x16_bf16 v[82:97], v[236:239], v[98:101], v[82:97]
	s_waitcnt lgkmcnt(0)
	v_mfma_f32_32x32x16_bf16 v[66:81], v[244:247], v[98:101], v[66:81]
	s_nop 9
	v_max_f32_e32 v235, v83, v83
	v_max_f32_e32 v236, v82, v82
	v_max_f32_e32 v235, v236, v235
	v_max3_f32 v235, v235, v84, v85
	v_max3_f32 v235, v235, v86, v87
	v_max3_f32 v235, v235, v88, v89
	v_max3_f32 v235, v235, v90, v91
	v_max3_f32 v235, v235, v92, v93
	v_max3_f32 v235, v235, v94, v95
	v_max3_f32 v235, v235, v96, v97
	v_max3_f32 v235, v235, v66, v67
	v_max3_f32 v235, v235, v68, v69
	v_max3_f32 v235, v235, v70, v71
	v_max3_f32 v235, v235, v72, v73
	v_max3_f32 v235, v235, v74, v75
	v_max3_f32 v235, v235, v76, v77
	v_max3_f32 v235, v235, v78, v79
	v_max3_f32 v235, v235, v80, v81
	ds_bpermute_b32 v236, v228, v235
	s_waitcnt lgkmcnt(0)
	v_max3_f32 v235, v218, v235, v236
	v_sub_f32_e32 v218, v218, v235
	v_exp_f32_e32 v218, v218
	s_nop 0
	v_cmp_neq_f32_e32 vcc, 1.0, v218
	s_cbranch_vccz .LBB0_1614
	v_pk_mul_f32 v[64:65], v[64:65], v[218:219] op_sel_hi:[1,0]
	v_pk_mul_f32 v[62:63], v[62:63], v[218:219] op_sel_hi:[1,0]
	v_pk_mul_f32 v[60:61], v[60:61], v[218:219] op_sel_hi:[1,0]
	v_pk_mul_f32 v[58:59], v[58:59], v[218:219] op_sel_hi:[1,0]
	v_pk_mul_f32 v[56:57], v[56:57], v[218:219] op_sel_hi:[1,0]
	v_pk_mul_f32 v[54:55], v[54:55], v[218:219] op_sel_hi:[1,0]
	v_pk_mul_f32 v[52:53], v[52:53], v[218:219] op_sel_hi:[1,0]
	v_pk_mul_f32 v[50:51], v[50:51], v[218:219] op_sel_hi:[1,0]
	v_pk_mul_f32 v[48:49], v[48:49], v[218:219] op_sel_hi:[1,0]
	v_pk_mul_f32 v[46:47], v[46:47], v[218:219] op_sel_hi:[1,0]
	v_pk_mul_f32 v[44:45], v[44:45], v[218:219] op_sel_hi:[1,0]
	v_pk_mul_f32 v[42:43], v[42:43], v[218:219] op_sel_hi:[1,0]
	v_pk_mul_f32 v[40:41], v[40:41], v[218:219] op_sel_hi:[1,0]
	v_pk_mul_f32 v[38:39], v[38:39], v[218:219] op_sel_hi:[1,0]
	v_pk_mul_f32 v[36:37], v[36:37], v[218:219] op_sel_hi:[1,0]
	v_pk_mul_f32 v[34:35], v[34:35], v[218:219] op_sel_hi:[1,0]
	v_pk_mul_f32 v[32:33], v[32:33], v[218:219] op_sel_hi:[1,0]
	v_pk_mul_f32 v[30:31], v[30:31], v[218:219] op_sel_hi:[1,0]
	v_pk_mul_f32 v[28:29], v[28:29], v[218:219] op_sel_hi:[1,0]
	v_pk_mul_f32 v[26:27], v[26:27], v[218:219] op_sel_hi:[1,0]
	v_pk_mul_f32 v[24:25], v[24:25], v[218:219] op_sel_hi:[1,0]
	v_pk_mul_f32 v[22:23], v[22:23], v[218:219] op_sel_hi:[1,0]
	v_pk_mul_f32 v[20:21], v[20:21], v[218:219] op_sel_hi:[1,0]
	v_pk_mul_f32 v[18:19], v[18:19], v[218:219] op_sel_hi:[1,0]
	v_pk_mul_f32 v[16:17], v[16:17], v[218:219] op_sel_hi:[1,0]
	v_pk_mul_f32 v[14:15], v[14:15], v[218:219] op_sel_hi:[1,0]
	v_pk_mul_f32 v[12:13], v[12:13], v[218:219] op_sel_hi:[1,0]
	v_pk_mul_f32 v[10:11], v[10:11], v[218:219] op_sel_hi:[1,0]
	v_pk_mul_f32 v[8:9], v[8:9], v[218:219] op_sel_hi:[1,0]
	v_pk_mul_f32 v[6:7], v[6:7], v[218:219] op_sel_hi:[1,0]
	v_pk_mul_f32 v[4:5], v[4:5], v[218:219] op_sel_hi:[1,0]
	v_pk_mul_f32 v[2:3], v[2:3], v[218:219] op_sel_hi:[1,0]

.LBB0_1618:
	v_xor_b32_e32 v226, 0x10000, v226
	v_xor_b32_e32 v227, 0x10000, v227
	s_waitcnt lgkmcnt(0)
	s_barrier
	s_waitcnt vmcnt(4)
	ds_write_b128 v229, v[146:149]
	s_waitcnt vmcnt(3)
	ds_write_b128 v230, v[150:153]
	s_waitcnt vmcnt(2)
	ds_write_b128 v231, v[154:157]
	s_waitcnt vmcnt(1)
	ds_write_b128 v232, v[162:165] offset:25600
	s_waitcnt vmcnt(0)
	ds_write_b128 v233, v[158:161] offset:25600
	v_mov_b32_e32 v218, v235
	s_add_i32 s99, s58, -1
	s_cmp_gt_i32 s99, s29
	s_cbranch_scc1 .Lmla_c2_skip
	v_add_u32_e32 v235, v226, v225
	ds_read_b128 v[66:69], v235
	ds_read_b128 v[236:239], v235 offset:32
	ds_read_b128 v[70:73], v235 offset:12800
	ds_read_b128 v[244:247], v235 offset:12832
	s_waitcnt lgkmcnt(3)
	v_mfma_f32_32x32x16_bf16 v[82:97], v[66:69], v[142:145], 0
	ds_read_b128 v[248:251], v235 offset:64
	ds_read_b128 v[252:255], v235 offset:12864
	s_waitcnt lgkmcnt(3)
	v_mfma_f32_32x32x16_bf16 v[66:81], v[70:73], v[142:145], 0
	v_mfma_f32_32x32x16_bf16 v[82:97], v[236:239], v[138:141], v[82:97]
	s_waitcnt lgkmcnt(2)
	v_mfma_f32_32x32x16_bf16 v[66:81], v[244:247], v[138:141], v[66:81]
	ds_read_b128 v[236:239], v235 offset:96
	ds_read_b128 v[244:247], v235 offset:12896
	s_waitcnt lgkmcnt(3)
	v_mfma_f32_32x32x16_bf16 v[82:97], v[248:251], v[134:137], v[82:97]
	s_waitcnt lgkmcnt(2)
	v_mfma_f32_32x32x16_bf16 v[66:81], v[252:255], v[134:137], v[66:81]
	ds_read_b128 v[248:251], v235 offset:128
	ds_read_b128 v[252:255], v235 offset:12928
	s_waitcnt lgkmcnt(3)
	v_mfma_f32_32x32x16_bf16 v[82:97], v[236:239], v[130:133], v[82:97]
	s_waitcnt lgkmcnt(2)
	v_mfma_f32_32x32x16_bf16 v[66:81], v[244:247], v[130:133], v[66:81]
	ds_read_b128 v[236:239], v235 offset:160
	ds_read_b128 v[244:247], v235 offset:12960
	s_waitcnt lgkmcnt(3)
	v_mfma_f32_32x32x16_bf16 v[82:97], v[248:251], v[126:129], v[82:97]
	s_waitcnt lgkmcnt(2)
	v_mfma_f32_32x32x16_bf16 v[66:81], v[252:255], v[126:129], v[66:81]
	ds_read_b128 v[248:251], v235 offset:192
	ds_read_b128 v[252:255], v235 offset:12992
	s_waitcnt lgkmcnt(3)
	v_mfma_f32_32x32x16_bf16 v[82:97], v[236:239], v[122:125], v[82:97]
	s_waitcnt lgkmcnt(2)
	v_mfma_f32_32x32x16_bf16 v[66:81], v[244:247], v[122:125], v[66:81]
	ds_read_b128 v[236:239], v235 offset:224
	ds_read_b128 v[244:247], v235 offset:13024
	s_waitcnt lgkmcnt(3)
	v_mfma_f32_32x32x16_bf16 v[82:97], v[248:251], v[118:121], v[82:97]
	s_waitcnt lgkmcnt(2)
	v_mfma_f32_32x32x16_bf16 v[66:81], v[252:255], v[118:121], v[66:81]
	ds_read_b128 v[248:251], v235 offset:256
	ds_read_b128 v[252:255], v235 offset:13056
	s_waitcnt lgkmcnt(3)
	v_mfma_f32_32x32x16_bf16 v[82:97], v[236:239], v[114:117], v[82:97]
	s_waitcnt lgkmcnt(2)
	v_mfma_f32_32x32x16_bf16 v[66:81], v[244:247], v[114:117], v[66:81]
	ds_read_b128 v[236:239], v235 offset:288
	ds_read_b128 v[244:247], v235 offset:13088
	s_waitcnt lgkmcnt(3)
	v_mfma_f32_32x32x16_bf16 v[82:97], v[248:251], v[110:113], v[82:97]
	s_waitcnt lgkmcnt(2)
	v_mfma_f32_32x32x16_bf16 v[66:81], v[252:255], v[110:113], v[66:81]
	ds_read_b128 v[248:251], v235 offset:320
	ds_read_b128 v[252:255], v235 offset:13120
	s_waitcnt lgkmcnt(3)
	v_mfma_f32_32x32x16_bf16 v[82:97], v[236:239], v[106:109], v[82:97]
	s_waitcnt lgkmcnt(2)
	v_mfma_f32_32x32x16_bf16 v[66:81], v[244:247], v[106:109], v[66:81]
	ds_read_b128 v[236:239], v235 offset:352
	ds_read_b128 v[244:247], v235 offset:13152
	s_waitcnt lgkmcnt(3)
	v_mfma_f32_32x32x16_bf16 v[82:97], v[248:251], v[102:105], v[82:97]
	s_waitcnt lgkmcnt(2)
	v_mfma_f32_32x32x16_bf16 v[66:81], v[252:255], v[102:105], v[66:81]
	s_waitcnt lgkmcnt(1)
	v_mfma_f32_32x32x16_bf16 v[82:97], v[236:239], v[98:101], v[82:97]
	s_waitcnt lgkmcnt(0)
	v_mfma_f32_32x32x16_bf16 v[66:81], v[244:247], v[98:101], v[66:81]
	s_nop 9
	v_max_f32_e32 v235, v83, v83
	v_max_f32_e32 v236, v82, v82
	v_max_f32_e32 v235, v236, v235
	v_max3_f32 v235, v235, v84, v85
	v_max3_f32 v235, v235, v86, v87
	v_max3_f32 v235, v235, v88, v89
	v_max3_f32 v235, v235, v90, v91
	v_max3_f32 v235, v235, v92, v93
	v_max3_f32 v235, v235, v94, v95
	v_max3_f32 v235, v235, v96, v97
	v_max3_f32 v235, v235, v66, v67
	v_max3_f32 v235, v235, v68, v69
	v_max3_f32 v235, v235, v70, v71
	v_max3_f32 v235, v235, v72, v73
	v_max3_f32 v235, v235, v74, v75
	v_max3_f32 v235, v235, v76, v77
	v_max3_f32 v235, v235, v78, v79
	v_max3_f32 v235, v235, v80, v81
	ds_bpermute_b32 v236, v228, v235
	s_waitcnt lgkmcnt(0)
	v_max3_f32 v235, v218, v235, v236
	v_sub_f32_e32 v218, v218, v235
	v_exp_f32_e32 v218, v218
	s_nop 0
	v_cmp_neq_f32_e32 vcc, 1.0, v218
	s_cbranch_vccz .Lmla_c2_1614
	v_pk_mul_f32 v[64:65], v[64:65], v[218:219] op_sel_hi:[1,0]
	v_pk_mul_f32 v[62:63], v[62:63], v[218:219] op_sel_hi:[1,0]
	v_pk_mul_f32 v[60:61], v[60:61], v[218:219] op_sel_hi:[1,0]
	v_pk_mul_f32 v[58:59], v[58:59], v[218:219] op_sel_hi:[1,0]
	v_pk_mul_f32 v[56:57], v[56:57], v[218:219] op_sel_hi:[1,0]
	v_pk_mul_f32 v[54:55], v[54:55], v[218:219] op_sel_hi:[1,0]
	v_pk_mul_f32 v[52:53], v[52:53], v[218:219] op_sel_hi:[1,0]
	v_pk_mul_f32 v[50:51], v[50:51], v[218:219] op_sel_hi:[1,0]
	v_pk_mul_f32 v[48:49], v[48:49], v[218:219] op_sel_hi:[1,0]
	v_pk_mul_f32 v[46:47], v[46:47], v[218:219] op_sel_hi:[1,0]
	v_pk_mul_f32 v[44:45], v[44:45], v[218:219] op_sel_hi:[1,0]
	v_pk_mul_f32 v[42:43], v[42:43], v[218:219] op_sel_hi:[1,0]
	v_pk_mul_f32 v[40:41], v[40:41], v[218:219] op_sel_hi:[1,0]
	v_pk_mul_f32 v[38:39], v[38:39], v[218:219] op_sel_hi:[1,0]
	v_pk_mul_f32 v[36:37], v[36:37], v[218:219] op_sel_hi:[1,0]
	v_pk_mul_f32 v[34:35], v[34:35], v[218:219] op_sel_hi:[1,0]
	v_pk_mul_f32 v[32:33], v[32:33], v[218:219] op_sel_hi:[1,0]
	v_pk_mul_f32 v[30:31], v[30:31], v[218:219] op_sel_hi:[1,0]
	v_pk_mul_f32 v[28:29], v[28:29], v[218:219] op_sel_hi:[1,0]
	v_pk_mul_f32 v[26:27], v[26:27], v[218:219] op_sel_hi:[1,0]
	v_pk_mul_f32 v[24:25], v[24:25], v[218:219] op_sel_hi:[1,0]
	v_pk_mul_f32 v[22:23], v[22:23], v[218:219] op_sel_hi:[1,0]
	v_pk_mul_f32 v[20:21], v[20:21], v[218:219] op_sel_hi:[1,0]
	v_pk_mul_f32 v[18:19], v[18:19], v[218:219] op_sel_hi:[1,0]
	v_pk_mul_f32 v[16:17], v[16:17], v[218:219] op_sel_hi:[1,0]
	v_pk_mul_f32 v[14:15], v[14:15], v[218:219] op_sel_hi:[1,0]
	v_pk_mul_f32 v[12:13], v[12:13], v[218:219] op_sel_hi:[1,0]
	v_pk_mul_f32 v[10:11], v[10:11], v[218:219] op_sel_hi:[1,0]
	v_pk_mul_f32 v[8:9], v[8:9], v[218:219] op_sel_hi:[1,0]
	v_pk_mul_f32 v[6:7], v[6:7], v[218:219] op_sel_hi:[1,0]
	v_pk_mul_f32 v[4:5], v[4:5], v[218:219] op_sel_hi:[1,0]
	v_pk_mul_f32 v[2:3], v[2:3], v[218:219] op_sel_hi:[1,0]

.Lmla_c2_done:
	v_xor_b32_e32 v226, 0x10000, v226
	v_xor_b32_e32 v227, 0x10000, v227
	s_andn2_b64 vcc, exec, s[48:49]
	s_waitcnt lgkmcnt(0)
	s_barrier
	s_cbranch_vccnz .LBB0_1597
	v_add_u32_e32 v162, v226, v225
	ds_read_b128 v[66:69], v162
	ds_read_b128 v[146:149], v162 offset:32
	ds_read_b128 v[70:73], v162 offset:12800
	ds_read_b128 v[150:153], v162 offset:12832
	s_waitcnt lgkmcnt(3)
	v_mfma_f32_32x32x16_bf16 v[82:97], v[66:69], v[142:145], 0
	ds_read_b128 v[154:157], v162 offset:64
	ds_read_b128 v[158:161], v162 offset:12864
	s_waitcnt lgkmcnt(3)
	v_mfma_f32_32x32x16_bf16 v[66:81], v[70:73], v[142:145], 0
	v_mfma_f32_32x32x16_bf16 v[82:97], v[146:149], v[138:141], v[82:97]
	ds_read_b128 v[142:145], v162 offset:96
	ds_read_b128 v[146:149], v162 offset:12896
	s_waitcnt lgkmcnt(4)
	v_mfma_f32_32x32x16_bf16 v[66:81], v[150:153], v[138:141], v[66:81]
	s_waitcnt lgkmcnt(3)
	v_mfma_f32_32x32x16_bf16 v[82:97], v[154:157], v[134:137], v[82:97]
	ds_read_b128 v[138:141], v162 offset:128
	ds_read_b128 v[150:153], v162 offset:12928
	s_waitcnt lgkmcnt(4)
	v_mfma_f32_32x32x16_bf16 v[66:81], v[158:161], v[134:137], v[66:81]
	s_waitcnt lgkmcnt(3)
	v_mfma_f32_32x32x16_bf16 v[82:97], v[142:145], v[130:133], v[82:97]
	ds_read_b128 v[134:137], v162 offset:160
	ds_read_b128 v[142:145], v162 offset:12960
	s_waitcnt lgkmcnt(4)
	v_mfma_f32_32x32x16_bf16 v[66:81], v[146:149], v[130:133], v[66:81]
	s_waitcnt lgkmcnt(3)
	v_mfma_f32_32x32x16_bf16 v[82:97], v[138:141], v[126:129], v[82:97]
	ds_read_b128 v[130:133], v162 offset:192
	ds_read_b128 v[138:141], v162 offset:12992
	s_waitcnt lgkmcnt(4)
	v_mfma_f32_32x32x16_bf16 v[66:81], v[150:153], v[126:129], v[66:81]
	s_waitcnt lgkmcnt(3)
	v_mfma_f32_32x32x16_bf16 v[82:97], v[134:137], v[122:125], v[82:97]
	ds_read_b128 v[126:129], v162 offset:224
	ds_read_b128 v[134:137], v162 offset:13024
	s_waitcnt lgkmcnt(4)
	v_mfma_f32_32x32x16_bf16 v[66:81], v[142:145], v[122:125], v[66:81]
	s_waitcnt lgkmcnt(3)
	v_mfma_f32_32x32x16_bf16 v[82:97], v[130:133], v[118:121], v[82:97]
	ds_read_b128 v[122:125], v162 offset:256
	ds_read_b128 v[130:133], v162 offset:13056
	s_waitcnt lgkmcnt(4)
	v_mfma_f32_32x32x16_bf16 v[66:81], v[138:141], v[118:121], v[66:81]
	s_waitcnt lgkmcnt(3)
	v_mfma_f32_32x32x16_bf16 v[82:97], v[126:129], v[114:117], v[82:97]
	ds_read_b128 v[118:121], v162 offset:288
	ds_read_b128 v[126:129], v162 offset:13088
	s_waitcnt lgkmcnt(4)
	v_mfma_f32_32x32x16_bf16 v[66:81], v[134:137], v[114:117], v[66:81]
	s_waitcnt lgkmcnt(3)
	v_mfma_f32_32x32x16_bf16 v[82:97], v[122:125], v[110:113], v[82:97]
	ds_read_b128 v[114:117], v162 offset:320
	ds_read_b128 v[122:125], v162 offset:13120
	s_waitcnt lgkmcnt(4)
	v_mfma_f32_32x32x16_bf16 v[66:81], v[130:133], v[110:113], v[66:81]
	s_waitcnt lgkmcnt(3)
	v_mfma_f32_32x32x16_bf16 v[82:97], v[118:121], v[106:109], v[82:97]
	ds_read_b128 v[110:113], v162 offset:352
	ds_read_b128 v[118:121], v162 offset:13152
	s_waitcnt lgkmcnt(4)
	v_mfma_f32_32x32x16_bf16 v[66:81], v[126:129], v[106:109], v[66:81]
	s_waitcnt lgkmcnt(3)
	v_mfma_f32_32x32x16_bf16 v[82:97], v[114:117], v[102:105], v[82:97]
	s_waitcnt lgkmcnt(2)
	v_mfma_f32_32x32x16_bf16 v[66:81], v[122:125], v[102:105], v[66:81]
	s_waitcnt lgkmcnt(1)
	v_mfma_f32_32x32x16_bf16 v[82:97], v[110:113], v[98:101], v[82:97]
	s_waitcnt lgkmcnt(0)
	v_mfma_f32_32x32x16_bf16 v[66:81], v[118:121], v[98:101], v[66:81]
	s_nop 9
	v_max_f32_e32 v98, v83, v83
	v_max_f32_e32 v99, v82, v82
	v_max_f32_e32 v98, v99, v98
	v_max3_f32 v98, v98, v84, v85
	v_max3_f32 v98, v98, v86, v87
	v_max3_f32 v98, v98, v88, v89
	v_max3_f32 v98, v98, v90, v91
	v_max3_f32 v98, v98, v92, v93
	v_max3_f32 v98, v98, v94, v95
	v_max3_f32 v98, v98, v96, v97
	v_max3_f32 v98, v98, v66, v67
	v_max3_f32 v98, v98, v68, v69
	v_max3_f32 v98, v98, v70, v71
	v_max3_f32 v98, v98, v72, v73
	v_max3_f32 v98, v98, v74, v75
	v_max3_f32 v98, v98, v76, v77
	v_max3_f32 v98, v98, v78, v79
	v_max3_f32 v98, v98, v80, v81
	ds_bpermute_b32 v99, v228, v98
	s_waitcnt lgkmcnt(0)
	v_max3_f32 v99, v235, v98, v99
	v_sub_f32_e32 v98, v235, v99
	v_exp_f32_e32 v98, v98
	s_nop 0
	v_cmp_neq_f32_e32 vcc, 1.0, v98
	s_cbranch_vccz .LBB0_1596
	v_pk_mul_f32 v[64:65], v[64:65], v[98:99] op_sel_hi:[1,0]
	v_pk_mul_f32 v[62:63], v[62:63], v[98:99] op_sel_hi:[1,0]
	v_pk_mul_f32 v[60:61], v[60:61], v[98:99] op_sel_hi:[1,0]
	v_pk_mul_f32 v[58:59], v[58:59], v[98:99] op_sel_hi:[1,0]
	v_pk_mul_f32 v[56:57], v[56:57], v[98:99] op_sel_hi:[1,0]
	v_pk_mul_f32 v[54:55], v[54:55], v[98:99] op_sel_hi:[1,0]
	v_pk_mul_f32 v[52:53], v[52:53], v[98:99] op_sel_hi:[1,0]
	v_pk_mul_f32 v[50:51], v[50:51], v[98:99] op_sel_hi:[1,0]
	v_pk_mul_f32 v[48:49], v[48:49], v[98:99] op_sel_hi:[1,0]
	v_pk_mul_f32 v[46:47], v[46:47], v[98:99] op_sel_hi:[1,0]
	v_pk_mul_f32 v[44:45], v[44:45], v[98:99] op_sel_hi:[1,0]
	v_pk_mul_f32 v[42:43], v[42:43], v[98:99] op_sel_hi:[1,0]
	v_pk_mul_f32 v[40:41], v[40:41], v[98:99] op_sel_hi:[1,0]
	v_pk_mul_f32 v[38:39], v[38:39], v[98:99] op_sel_hi:[1,0]
	v_pk_mul_f32 v[36:37], v[36:37], v[98:99] op_sel_hi:[1,0]
	v_pk_mul_f32 v[34:35], v[34:35], v[98:99] op_sel_hi:[1,0]
	v_pk_mul_f32 v[32:33], v[32:33], v[98:99] op_sel_hi:[1,0]
	v_pk_mul_f32 v[30:31], v[30:31], v[98:99] op_sel_hi:[1,0]
	v_pk_mul_f32 v[28:29], v[28:29], v[98:99] op_sel_hi:[1,0]
	v_pk_mul_f32 v[26:27], v[26:27], v[98:99] op_sel_hi:[1,0]
	v_pk_mul_f32 v[24:25], v[24:25], v[98:99] op_sel_hi:[1,0]
	v_pk_mul_f32 v[22:23], v[22:23], v[98:99] op_sel_hi:[1,0]
	v_pk_mul_f32 v[20:21], v[20:21], v[98:99] op_sel_hi:[1,0]
	v_pk_mul_f32 v[18:19], v[18:19], v[98:99] op_sel_hi:[1,0]
	v_pk_mul_f32 v[16:17], v[16:17], v[98:99] op_sel_hi:[1,0]
	v_pk_mul_f32 v[14:15], v[14:15], v[98:99] op_sel_hi:[1,0]
	v_pk_mul_f32 v[12:13], v[12:13], v[98:99] op_sel_hi:[1,0]
	v_pk_mul_f32 v[10:11], v[10:11], v[98:99] op_sel_hi:[1,0]
	v_pk_mul_f32 v[8:9], v[8:9], v[98:99] op_sel_hi:[1,0]
	v_pk_mul_f32 v[6:7], v[6:7], v[98:99] op_sel_hi:[1,0]
	v_pk_mul_f32 v[4:5], v[4:5], v[98:99] op_sel_hi:[1,0]
	v_pk_mul_f32 v[2:3], v[2:3], v[98:99] op_sel_hi:[1,0]
	s_branch .LBB0_1596
